# out-proj: bf16 residual prefetched at phase start and used as accumulator init (layers 1-3), epilogue vmcnt waits moved behind the first-layer loads only
# speedup vs baseline: 1.1154x; 1.0071x over previous
.LBB0_291:
	v_readlane_b32 s0, v252, 26
	v_mov_b32_e32 v12, v212
	v_readlane_b32 s1, v252, 27
	s_andn2_b64 vcc, exec, s[0:1]
	v_readfirstlane_b32 s9, v12
	s_cbranch_vccnz .LBB0_479
	s_add_i32 s0, s94, 1
	s_cmp_gt_u32 s0, 4
	s_cbranch_scc0 .Lrpf_skip
	v_readlane_b32 s0, v251, 25
	v_readlane_b32 s1, v251, 14
	s_lshr_b32 s4, s9, 8
	s_bfe_u32 s5, s9, 0x20006
	s_lshl_b32 s0, s0, 8
	s_lshl_b32 s4, s4, 6
	s_add_i32 s0, s0, s4
	s_lshl_b32 s1, s1, 8
	s_lshl_b32 s5, s5, 5
	s_add_i32 s1, s1, s5
	s_lshl_b32 s0, s0, 11
	s_lshl_b32 s1, s1, 1
	s_add_i32 s0, s0, s1
	s_add_u32 s6, s28, s0
	s_addc_u32 s7, s29, 0
	v_and_b32_e32 v234, 15, v12
	v_bfe_u32 v235, v12, 4, 2
	v_lshlrev_b32_e32 v234, 11, v234
	v_lshl_add_u32 v234, v235, 4, v234
	v_mov_b32_e32 v102, v234
	global_load_dwordx4 v[98:101], v102, s[6:7]
	global_load_dwordx4 v[102:105], v102, s[6:7] offset:256
	v_add_u32_e32 v110, 0x8000, v234
	global_load_dwordx4 v[106:109], v110, s[6:7]
	global_load_dwordx4 v[110:113], v110, s[6:7] offset:256
	v_add_u32_e32 v118, 0x10000, v234
	global_load_dwordx4 v[114:117], v118, s[6:7]
	global_load_dwordx4 v[118:121], v118, s[6:7] offset:256
	v_add_u32_e32 v126, 0x18000, v234
	global_load_dwordx4 v[122:125], v126, s[6:7]
	global_load_dwordx4 v[126:129], v126, s[6:7] offset:256
	v_add_u32_e32 v166, 0x40000, v234
	global_load_dwordx4 v[162:165], v166, s[6:7]
	global_load_dwordx4 v[166:169], v166, s[6:7] offset:256
	v_add_u32_e32 v198, 0x48000, v234
	global_load_dwordx4 v[194:197], v198, s[6:7]
	global_load_dwordx4 v[198:201], v198, s[6:7] offset:256
	v_add_u32_e32 v206, 0x50000, v234
	global_load_dwordx4 v[202:205], v206, s[6:7]
	global_load_dwordx4 v[206:209], v206, s[6:7] offset:256
	v_add_u32_e32 v234, 0x58000, v234
	global_load_dwordx4 v[230:233], v234, s[6:7]
	global_load_dwordx4 v[234:237], v234, s[6:7] offset:256
.Lrpf_skip:
	v_lshlrev_b32_e32 v0, 4, v12
	v_add_u32_e32 v2, 0x2000, v0
	s_waitcnt lgkmcnt(0)
	v_ashrrev_i32_e32 v3, 31, v2
	v_lshrrev_b32_e32 v3, 22, v3
	v_add_u32_e32 v3, v2, v3
	v_ashrrev_i32_e32 v6, 10, v3
	v_mul_i32_i24_e32 v3, 0x400, v6
	v_sub_u32_e32 v2, v2, v3
	v_lshrrev_b32_e32 v3, 4, v2
	v_bitop3_b32 v2, v3, v2, 32 bitop3:0x6c
	v_ashrrev_i32_e32 v3, 31, v2
	v_lshrrev_b32_e32 v3, 26, v3
	v_add_u32_e32 v3, v2, v3
	v_lshlrev_b32_e32 v4, 3, v6
	s_ashr_i32 s17, s16, 31
	v_ashrrev_i32_e32 v7, 6, v3
	v_and_b32_e32 v4, -16, v4
	s_lshl_b64 s[0:1], s[16:17], 21
	v_add_u32_e32 v4, v7, v4
	s_add_u32 s44, s96, s0
	v_and_b32_e32 v5, 3, v7
	s_mov_b32 s0, 0x1fffe0
	v_lshrrev_b32_e32 v8, 2, v4
	v_lshlrev_b32_e32 v9, 1, v4
	v_and_b32_e32 v3, 0xc0, v3
	v_and_or_b32 v5, v4, s0, v5
	v_and_b32_e32 v8, 4, v8
	v_and_b32_e32 v9, 24, v9
	v_sub_u32_e32 v2, v2, v3
	v_or3_b32 v5, v5, v8, v9
	v_lshlrev_b32_e32 v8, 5, v6
	v_ashrrev_i16_sdwa v2, v217, sext(v2) dst_sel:DWORD dst_unused:UNUSED_PAD src0_sel:DWORD src1_sel:BYTE_0
	v_and_b32_e32 v9, 32, v8
	v_bfe_i32 v8, v2, 0, 16
	v_add_lshl_u32 v2, v9, v8, 1
	v_lshl_add_u32 v184, v5, 11, v2
	v_lshl_add_u32 v186, v4, 11, v2
	v_bfe_i32 v2, v12, 27, 1
	v_lshrrev_b32_e32 v2, 22, v2
	v_add_u32_e32 v2, v0, v2
	v_and_b32_e32 v2, 0xfffffc00, v2
	v_sub_u32_e32 v0, v0, v2
	v_lshrrev_b32_e32 v2, 4, v0
	v_ashrrev_i32_e32 v3, 31, v12
	v_bitop3_b32 v0, v2, v0, 32 bitop3:0x6c
	v_lshrrev_b32_e32 v3, 26, v3
	v_ashrrev_i32_e32 v2, 31, v0
	v_add_u32_e32 v3, v12, v3
	v_lshrrev_b32_e32 v2, 26, v2
	v_ashrrev_i32_e32 v10, 6, v3
	v_add_u32_e32 v2, v0, v2
	v_lshlrev_b32_e32 v3, 3, v10
	v_ashrrev_i32_e32 v9, 6, v2
	v_and_b32_e32 v3, -16, v3
	v_add_u32_e32 v3, v9, v3
	v_and_b32_e32 v4, 3, v9
	v_lshrrev_b32_e32 v5, 2, v3
	v_lshlrev_b32_e32 v11, 1, v3
	v_and_b32_e32 v2, 0xc0, v2
	s_addc_u32 s45, s97, s1
	s_ashr_i32 s10, s9, 6
	v_and_or_b32 v4, v3, s0, v4
	v_and_b32_e32 v5, 4, v5
	v_and_b32_e32 v11, 24, v11
	v_sub_u32_e32 v0, v0, v2
	s_ashr_i32 s8, s9, 8
	s_lshl_b32 s46, s10, 10
	v_or3_b32 v4, v4, v5, v11
	v_lshlrev_b32_e32 v5, 5, v10
	v_ashrrev_i16_sdwa v0, v217, sext(v0) dst_sel:DWORD dst_unused:UNUSED_PAD src0_sel:DWORD src1_sel:BYTE_0
	v_readlane_b32 s0, v251, 23
	v_and_b32_e32 v5, 32, v5
	v_bfe_i32 v11, v0, 0, 16
	v_readlane_b32 s1, v251, 24
	s_add_u32 s24, s44, s0
	v_add_lshl_u32 v2, v5, v11, 1
	s_addc_u32 s25, s45, s1
	s_add_i32 s47, s46, 0
	v_lshl_add_u32 v0, v4, 11, v2
	s_add_i32 m0, s47, 0x10000
	v_lshl_add_u32 v188, v3, 11, v2
	global_load_lds_dwordx4 v0, s[24:25]
	s_add_i32 m0, s47, 0x12000
	s_add_u32 s0, s24, 0x40000
	global_load_lds_dwordx4 v184, s[24:25]
	s_addc_u32 s1, s25, 0
	s_add_i32 m0, s47, 0x14000
	s_add_i32 s48, s47, 0x2000
	global_load_lds_dwordx4 v0, s[0:1]
	s_add_i32 m0, s47, 0x16000
	s_add_i32 s49, s47, 0x4000
	global_load_lds_dwordx4 v184, s[0:1]
	v_readlane_b32 s0, v251, 31
	s_mov_b32 m0, s47
	v_readlane_b32 s1, v251, 32
	s_add_i32 s50, s47, 0x6000
	v_mov_b32_e32 v185, v1
	s_cmp_eq_u32 s8, 1
	s_mov_b32 s93, s92
	s_mov_b32 s92, s16
	global_load_lds_dwordx4 v188, s[0:1]
	s_mov_b32 m0, s48
	v_lshl_add_u64 v[2:3], s[24:25], 0, v[0:1]
	global_load_lds_dwordx4 v186, s[0:1]
	v_readlane_b32 s0, v251, 33
	s_mov_b32 m0, s49
	v_readlane_b32 s1, v251, 34
	v_lshl_add_u64 v[4:5], s[24:25], 0, v[184:185]
	s_nop 3
	global_load_lds_dwordx4 v188, s[0:1]
	s_mov_b32 m0, s50
	s_nop 0
	global_load_lds_dwordx4 v186, s[0:1]
	v_readlane_b32 s0, v252, 2
	v_readlane_b32 s1, v252, 3
	s_load_dword s51, s[0:1], 0x0
	s_cselect_b64 s[0:1], -1, 0
	s_cmp_lg_u32 s8, 1
	s_cbranch_scc1 .LBB0_294
	s_barrier

.LBB0_303:
	s_ashr_i32 s17, s16, 31
	s_lshl_b64 s[18:19], s[16:17], 19
	v_readlane_b32 s20, v251, 27
	v_readlane_b32 s21, v251, 28
	s_add_u32 s18, s20, s18
	s_addc_u32 s19, s21, s19
	s_and_b64 s[20:21], s[36:37], exec
	s_cselect_b32 s17, s19, s23
	s_cselect_b32 s40, s18, s22
	s_ashr_i32 s13, s12, 31
	s_lshl_b64 s[20:21], s[12:13], 19
	s_add_u32 s20, s44, s20
	s_addc_u32 s21, s45, s21
	s_and_b64 s[38:39], s[36:37], exec
	s_cselect_b32 s13, s21, s25
	s_cselect_b32 s41, s20, s24
	s_add_u32 s22, s22, 0x40080
	s_addc_u32 s23, s23, 0
	s_add_u32 s42, s24, 0x100
	v_mov_b32_e32 v2, 0
	s_addc_u32 s43, s25, 0
	s_mov_b32 s61, -2
	s_waitcnt lgkmcnt(0)
	v_mov_b32_e32 v3, v2
	v_mov_b32_e32 v4, v2
	v_mov_b32_e32 v5, v2
	v_mov_b32_e32 v6, v2
	v_mov_b32_e32 v7, v2
	v_mov_b32_e32 v8, v2
	v_mov_b32_e32 v9, v2
	v_mov_b32_e32 v18, v2
	v_mov_b32_e32 v19, v2
	v_mov_b32_e32 v20, v2
	v_mov_b32_e32 v21, v2
	v_mov_b32_e32 v22, v2
	v_mov_b32_e32 v23, v2
	v_mov_b32_e32 v24, v2
	v_mov_b32_e32 v25, v2
	v_mov_b32_e32 v34, v2
	v_mov_b32_e32 v35, v2
	v_mov_b32_e32 v36, v2
	v_mov_b32_e32 v37, v2
	v_mov_b32_e32 v38, v2
	v_mov_b32_e32 v39, v2
	v_mov_b32_e32 v40, v2
	v_mov_b32_e32 v41, v2
	v_mov_b32_e32 v50, v2
	v_mov_b32_e32 v51, v2
	v_mov_b32_e32 v52, v2
	v_mov_b32_e32 v53, v2
	v_mov_b32_e32 v54, v2
	v_mov_b32_e32 v55, v2
	v_mov_b32_e32 v56, v2
	v_mov_b32_e32 v57, v2
	v_mov_b32_e32 v10, v2
	v_mov_b32_e32 v11, v2
	v_mov_b32_e32 v12, v2
	v_mov_b32_e32 v13, v2
	v_mov_b32_e32 v14, v2
	v_mov_b32_e32 v15, v2
	v_mov_b32_e32 v16, v2
	v_mov_b32_e32 v17, v2
	v_mov_b32_e32 v26, v2
	v_mov_b32_e32 v27, v2
	v_mov_b32_e32 v28, v2
	v_mov_b32_e32 v29, v2
	v_mov_b32_e32 v30, v2
	v_mov_b32_e32 v31, v2
	v_mov_b32_e32 v32, v2
	v_mov_b32_e32 v33, v2
	v_mov_b32_e32 v42, v2
	v_mov_b32_e32 v43, v2
	v_mov_b32_e32 v44, v2
	v_mov_b32_e32 v45, v2
	v_mov_b32_e32 v46, v2
	v_mov_b32_e32 v47, v2
	v_mov_b32_e32 v48, v2
	v_mov_b32_e32 v49, v2
	v_mov_b32_e32 v58, v2
	v_mov_b32_e32 v59, v2
	v_mov_b32_e32 v60, v2
	v_mov_b32_e32 v61, v2
	v_mov_b32_e32 v62, v2
	v_mov_b32_e32 v63, v2
	v_mov_b32_e32 v64, v2
	v_mov_b32_e32 v65, v2
	v_mov_b32_e32 v66, v2
	v_mov_b32_e32 v67, v2
	v_mov_b32_e32 v68, v2
	v_mov_b32_e32 v69, v2
	v_mov_b32_e32 v70, v2
	v_mov_b32_e32 v71, v2
	v_mov_b32_e32 v72, v2
	v_mov_b32_e32 v73, v2
	v_mov_b32_e32 v82, v2
	v_mov_b32_e32 v83, v2
	v_mov_b32_e32 v84, v2
	v_mov_b32_e32 v85, v2
	v_mov_b32_e32 v86, v2
	v_mov_b32_e32 v87, v2
	v_mov_b32_e32 v88, v2
	v_mov_b32_e32 v89, v2
	v_mov_b32_e32 v130, v2
	v_mov_b32_e32 v131, v2
	v_mov_b32_e32 v132, v2
	v_mov_b32_e32 v133, v2
	v_mov_b32_e32 v134, v2
	v_mov_b32_e32 v135, v2
	v_mov_b32_e32 v136, v2
	v_mov_b32_e32 v137, v2
	v_mov_b32_e32 v146, v2
	v_mov_b32_e32 v147, v2
	v_mov_b32_e32 v148, v2
	v_mov_b32_e32 v149, v2
	v_mov_b32_e32 v150, v2
	v_mov_b32_e32 v151, v2
	v_mov_b32_e32 v152, v2
	v_mov_b32_e32 v153, v2
	v_mov_b32_e32 v74, v2
	v_mov_b32_e32 v75, v2
	v_mov_b32_e32 v76, v2
	v_mov_b32_e32 v77, v2
	v_mov_b32_e32 v78, v2
	v_mov_b32_e32 v79, v2
	v_mov_b32_e32 v80, v2
	v_mov_b32_e32 v81, v2
	v_mov_b32_e32 v90, v2
	v_mov_b32_e32 v91, v2
	v_mov_b32_e32 v92, v2
	v_mov_b32_e32 v93, v2
	v_mov_b32_e32 v94, v2
	v_mov_b32_e32 v95, v2
	v_mov_b32_e32 v96, v2
	v_mov_b32_e32 v97, v2
	v_mov_b32_e32 v138, v2
	v_mov_b32_e32 v139, v2
	v_mov_b32_e32 v140, v2
	v_mov_b32_e32 v141, v2
	v_mov_b32_e32 v142, v2
	v_mov_b32_e32 v143, v2
	v_mov_b32_e32 v144, v2
	v_mov_b32_e32 v145, v2
	v_mov_b32_e32 v154, v2
	v_mov_b32_e32 v155, v2
	v_mov_b32_e32 v156, v2
	v_mov_b32_e32 v157, v2
	v_mov_b32_e32 v158, v2
	v_mov_b32_e32 v159, v2
	v_mov_b32_e32 v160, v2
	v_mov_b32_e32 v161, v2
	s_and_b64 vcc, exec, s[4:5]
	s_cbranch_vccz .Lrpf_noinit
	s_waitcnt vmcnt(12)
	v_lshlrev_b32_e32 v158, 16, v98
	v_and_b32_e32 v159, 0xffff0000, v98
	v_lshlrev_b32_e32 v160, 16, v99
	v_and_b32_e32 v161, 0xffff0000, v99
	v_lshlrev_b32_e32 v154, 16, v100
	v_and_b32_e32 v155, 0xffff0000, v100
	v_lshlrev_b32_e32 v156, 16, v101
	v_and_b32_e32 v157, 0xffff0000, v101
	v_lshlrev_b32_e32 v150, 16, v102
	v_and_b32_e32 v151, 0xffff0000, v102
	v_lshlrev_b32_e32 v152, 16, v103
	v_and_b32_e32 v153, 0xffff0000, v103
	v_lshlrev_b32_e32 v146, 16, v104
	v_and_b32_e32 v147, 0xffff0000, v104
	v_lshlrev_b32_e32 v148, 16, v105
	v_and_b32_e32 v149, 0xffff0000, v105
	v_lshlrev_b32_e32 v142, 16, v106
	v_and_b32_e32 v143, 0xffff0000, v106
	v_lshlrev_b32_e32 v144, 16, v107
	v_and_b32_e32 v145, 0xffff0000, v107
	v_lshlrev_b32_e32 v138, 16, v108
	v_and_b32_e32 v139, 0xffff0000, v108
	v_lshlrev_b32_e32 v140, 16, v109
	v_and_b32_e32 v141, 0xffff0000, v109
	v_lshlrev_b32_e32 v134, 16, v110
	v_and_b32_e32 v135, 0xffff0000, v110
	v_lshlrev_b32_e32 v136, 16, v111
	v_and_b32_e32 v137, 0xffff0000, v111
	v_lshlrev_b32_e32 v130, 16, v112
	v_and_b32_e32 v131, 0xffff0000, v112
	v_lshlrev_b32_e32 v132, 16, v113
	v_and_b32_e32 v133, 0xffff0000, v113
	v_lshlrev_b32_e32 v94, 16, v114
	v_and_b32_e32 v95, 0xffff0000, v114
	v_lshlrev_b32_e32 v96, 16, v115
	v_and_b32_e32 v97, 0xffff0000, v115
	v_lshlrev_b32_e32 v90, 16, v116
	v_and_b32_e32 v91, 0xffff0000, v116
	v_lshlrev_b32_e32 v92, 16, v117
	v_and_b32_e32 v93, 0xffff0000, v117
	v_lshlrev_b32_e32 v86, 16, v118
	v_and_b32_e32 v87, 0xffff0000, v118
	v_lshlrev_b32_e32 v88, 16, v119
	v_and_b32_e32 v89, 0xffff0000, v119
	v_lshlrev_b32_e32 v82, 16, v120
	v_and_b32_e32 v83, 0xffff0000, v120
	v_lshlrev_b32_e32 v84, 16, v121
	v_and_b32_e32 v85, 0xffff0000, v121
	v_lshlrev_b32_e32 v78, 16, v122
	v_and_b32_e32 v79, 0xffff0000, v122
	v_lshlrev_b32_e32 v80, 16, v123
	v_and_b32_e32 v81, 0xffff0000, v123
	v_lshlrev_b32_e32 v74, 16, v124
	v_and_b32_e32 v75, 0xffff0000, v124
	v_lshlrev_b32_e32 v76, 16, v125
	v_and_b32_e32 v77, 0xffff0000, v125
	v_lshlrev_b32_e32 v70, 16, v126
	v_and_b32_e32 v71, 0xffff0000, v126
	v_lshlrev_b32_e32 v72, 16, v127
	v_and_b32_e32 v73, 0xffff0000, v127
	v_lshlrev_b32_e32 v66, 16, v128
	v_and_b32_e32 v67, 0xffff0000, v128
	v_lshlrev_b32_e32 v68, 16, v129
	v_and_b32_e32 v69, 0xffff0000, v129
	v_lshlrev_b32_e32 v62, 16, v162
	v_and_b32_e32 v63, 0xffff0000, v162
	v_lshlrev_b32_e32 v64, 16, v163
	v_and_b32_e32 v65, 0xffff0000, v163
	v_lshlrev_b32_e32 v58, 16, v164
	v_and_b32_e32 v59, 0xffff0000, v164
	v_lshlrev_b32_e32 v60, 16, v165
	v_and_b32_e32 v61, 0xffff0000, v165
	v_lshlrev_b32_e32 v54, 16, v166
	v_and_b32_e32 v55, 0xffff0000, v166
	v_lshlrev_b32_e32 v56, 16, v167
	v_and_b32_e32 v57, 0xffff0000, v167
	v_lshlrev_b32_e32 v50, 16, v168
	v_and_b32_e32 v51, 0xffff0000, v168
	v_lshlrev_b32_e32 v52, 16, v169
	v_and_b32_e32 v53, 0xffff0000, v169
	v_lshlrev_b32_e32 v46, 16, v194
	v_and_b32_e32 v47, 0xffff0000, v194
	v_lshlrev_b32_e32 v48, 16, v195
	v_and_b32_e32 v49, 0xffff0000, v195
	v_lshlrev_b32_e32 v42, 16, v196
	v_and_b32_e32 v43, 0xffff0000, v196
	v_lshlrev_b32_e32 v44, 16, v197
	v_and_b32_e32 v45, 0xffff0000, v197
	v_lshlrev_b32_e32 v38, 16, v198
	v_and_b32_e32 v39, 0xffff0000, v198
	v_lshlrev_b32_e32 v40, 16, v199
	v_and_b32_e32 v41, 0xffff0000, v199
	v_lshlrev_b32_e32 v34, 16, v200
	v_and_b32_e32 v35, 0xffff0000, v200
	v_lshlrev_b32_e32 v36, 16, v201
	v_and_b32_e32 v37, 0xffff0000, v201
	v_lshlrev_b32_e32 v30, 16, v202
	v_and_b32_e32 v31, 0xffff0000, v202
	v_lshlrev_b32_e32 v32, 16, v203
	v_and_b32_e32 v33, 0xffff0000, v203
	v_lshlrev_b32_e32 v26, 16, v204
	v_and_b32_e32 v27, 0xffff0000, v204
	v_lshlrev_b32_e32 v28, 16, v205
	v_and_b32_e32 v29, 0xffff0000, v205
	v_lshlrev_b32_e32 v22, 16, v206
	v_and_b32_e32 v23, 0xffff0000, v206
	v_lshlrev_b32_e32 v24, 16, v207
	v_and_b32_e32 v25, 0xffff0000, v207
	v_lshlrev_b32_e32 v18, 16, v208
	v_and_b32_e32 v19, 0xffff0000, v208
	v_lshlrev_b32_e32 v20, 16, v209
	v_and_b32_e32 v21, 0xffff0000, v209
	v_lshlrev_b32_e32 v14, 16, v230
	v_and_b32_e32 v15, 0xffff0000, v230
	v_lshlrev_b32_e32 v16, 16, v231
	v_and_b32_e32 v17, 0xffff0000, v231
	v_lshlrev_b32_e32 v10, 16, v232
	v_and_b32_e32 v11, 0xffff0000, v232
	v_lshlrev_b32_e32 v12, 16, v233
	v_and_b32_e32 v13, 0xffff0000, v233
	v_lshlrev_b32_e32 v6, 16, v234
	v_and_b32_e32 v7, 0xffff0000, v234
	v_lshlrev_b32_e32 v8, 16, v235
	v_and_b32_e32 v9, 0xffff0000, v235
	v_lshlrev_b32_e32 v2, 16, v236
	v_and_b32_e32 v3, 0xffff0000, v236
	v_lshlrev_b32_e32 v4, 16, v237
	v_and_b32_e32 v5, 0xffff0000, v237
.Lrpf_noinit:
.LBB0_304:
	s_add_u32 s24, s22, 0xfffc0080
	s_addc_u32 s25, s23, -1
	s_add_i32 s62, 0, 0x10000
	s_cmp_eq_u32 s61, 12
	s_cselect_b32 s39, s17, s25
	s_cselect_b32 s38, s40, s24
	s_cselect_b32 s25, s13, s43
	s_cselect_b32 s24, s41, s42
	s_add_i32 s64, 0, 0x14000
	v_add_u32_e32 v110, s62, v227
	v_add_u32_e32 v126, s64, v227
	ds_read_b128 v[98:101], v110
	ds_read_b128 v[102:105], v110 offset:1024
	ds_read_b128 v[106:109], v110 offset:2048
	ds_read_b128 v[110:113], v110 offset:3072
	ds_read_b128 v[114:117], v126
	ds_read_b128 v[118:121], v126 offset:1024
	ds_read_b128 v[122:125], v126 offset:2048
	ds_read_b128 v[126:129], v126 offset:3072
	v_lshl_add_u64 v[210:211], s[22:23], 0, v[190:191]
	s_add_i32 m0, s47, 0xc000
	ds_read_b128 v[162:165], v228
	ds_read_b128 v[166:169], v228 offset:1024
	ds_read_b128 v[194:197], v228 offset:2048
	ds_read_b128 v[198:201], v228 offset:3072
	ds_read_b128 v[202:205], v228 offset:4096
	ds_read_b128 v[206:209], v228 offset:5120
	ds_read_b128 v[230:233], v228 offset:6144
	ds_read_b128 v[234:237], v228 offset:7168
	global_load_lds_dwordx4 v[210:211], off
	v_lshl_add_u64 v[210:211], s[22:23], 0, v[192:193]
	s_add_i32 m0, s47, 0xe000
	s_nop 0
	global_load_lds_dwordx4 v[210:211], off
	s_waitcnt vmcnt(8)
	s_waitcnt lgkmcnt(0)
	s_barrier
	s_setprio 1
	s_waitcnt lgkmcnt(0)
	v_mfma_f32_16x16x32_bf16 v[158:161], v[98:101], v[162:165], v[158:161]
	v_mfma_f32_16x16x32_bf16 v[154:157], v[106:109], v[162:165], v[154:157]
	v_mfma_f32_16x16x32_bf16 v[142:145], v[98:101], v[194:197], v[142:145]
	v_mfma_f32_16x16x32_bf16 v[138:141], v[106:109], v[194:197], v[138:141]
	v_mfma_f32_16x16x32_bf16 v[94:97], v[98:101], v[202:205], v[94:97]
	v_mfma_f32_16x16x32_bf16 v[90:93], v[106:109], v[202:205], v[90:93]
	v_mfma_f32_16x16x32_bf16 v[78:81], v[98:101], v[230:233], v[78:81]
	v_mfma_f32_16x16x32_bf16 v[74:77], v[106:109], v[230:233], v[74:77]
	v_mfma_f32_16x16x32_bf16 v[158:161], v[102:105], v[166:169], v[158:161]
	v_mfma_f32_16x16x32_bf16 v[154:157], v[110:113], v[166:169], v[154:157]
	v_mfma_f32_16x16x32_bf16 v[142:145], v[102:105], v[198:201], v[142:145]
	v_mfma_f32_16x16x32_bf16 v[138:141], v[110:113], v[198:201], v[138:141]
	v_mfma_f32_16x16x32_bf16 v[94:97], v[102:105], v[206:209], v[94:97]
	v_mfma_f32_16x16x32_bf16 v[90:93], v[110:113], v[206:209], v[90:93]
	v_mfma_f32_16x16x32_bf16 v[78:81], v[102:105], v[234:237], v[78:81]
	v_mfma_f32_16x16x32_bf16 v[74:77], v[110:113], v[234:237], v[74:77]
	s_setprio 0
	s_setprio 1
	v_mfma_f32_16x16x32_bf16 v[150:153], v[114:117], v[162:165], v[150:153]
	v_mfma_f32_16x16x32_bf16 v[146:149], v[122:125], v[162:165], v[146:149]
	v_mfma_f32_16x16x32_bf16 v[134:137], v[114:117], v[194:197], v[134:137]
	v_mfma_f32_16x16x32_bf16 v[130:133], v[122:125], v[194:197], v[130:133]
	v_mfma_f32_16x16x32_bf16 v[86:89], v[114:117], v[202:205], v[86:89]
	v_mfma_f32_16x16x32_bf16 v[82:85], v[122:125], v[202:205], v[82:85]
	v_mfma_f32_16x16x32_bf16 v[70:73], v[114:117], v[230:233], v[70:73]
	v_mfma_f32_16x16x32_bf16 v[66:69], v[122:125], v[230:233], v[66:69]
	v_mfma_f32_16x16x32_bf16 v[150:153], v[118:121], v[166:169], v[150:153]
	v_mfma_f32_16x16x32_bf16 v[146:149], v[126:129], v[166:169], v[146:149]
	v_mfma_f32_16x16x32_bf16 v[134:137], v[118:121], v[198:201], v[134:137]
	v_mfma_f32_16x16x32_bf16 v[130:133], v[126:129], v[198:201], v[130:133]
	v_mfma_f32_16x16x32_bf16 v[86:89], v[118:121], v[206:209], v[86:89]
	v_mfma_f32_16x16x32_bf16 v[82:85], v[126:129], v[206:209], v[82:85]
	v_mfma_f32_16x16x32_bf16 v[70:73], v[118:121], v[234:237], v[70:73]
	v_mfma_f32_16x16x32_bf16 v[66:69], v[126:129], v[234:237], v[66:69]
	s_setprio 0
	s_barrier
	s_add_i32 s62, s62, s46
	v_lshl_add_u64 v[210:211], s[24:25], 0, v[0:1]
	s_mov_b32 m0, s62
	ds_read_b128 v[162:165], v228 offset:16384
	ds_read_b128 v[166:169], v228 offset:17408
	ds_read_b128 v[194:197], v228 offset:18432
	ds_read_b128 v[198:201], v228 offset:19456
	ds_read_b128 v[202:205], v228 offset:20480
	ds_read_b128 v[206:209], v228 offset:21504
	ds_read_b128 v[230:233], v228 offset:22528
	ds_read_b128 v[234:237], v228 offset:23552
	global_load_lds_dwordx4 v[210:211], off
	s_add_i32 m0, s62, 0x2000
	s_add_u32 s62, s24, 0x40000
	v_lshl_add_u64 v[238:239], s[24:25], 0, v[184:185]
	s_addc_u32 s63, s25, 0
	s_add_i32 s64, s64, s46
	global_load_lds_dwordx4 v[238:239], off
	v_lshl_add_u64 v[240:241], s[62:63], 0, v[0:1]
	s_mov_b32 m0, s64
	v_lshl_add_u64 v[242:243], s[38:39], 0, v[186:187]
	global_load_lds_dwordx4 v[240:241], off
	v_lshl_add_u64 v[240:241], s[62:63], 0, v[184:185]
	s_add_i32 m0, s64, 0x2000
	s_nop 0
	global_load_lds_dwordx4 v[240:241], off
	v_lshl_add_u64 v[240:241], s[38:39], 0, v[188:189]
	s_mov_b32 m0, s47
	s_nop 0
	global_load_lds_dwordx4 v[240:241], off
	s_mov_b32 m0, s48
	s_nop 0
	global_load_lds_dwordx4 v[242:243], off
	s_waitcnt vmcnt(8)
	s_waitcnt lgkmcnt(0)
	s_barrier
	s_setprio 1
	s_waitcnt lgkmcnt(0)
	v_mfma_f32_16x16x32_bf16 v[62:65], v[98:101], v[162:165], v[62:65]
	v_mfma_f32_16x16x32_bf16 v[58:61], v[106:109], v[162:165], v[58:61]
	v_mfma_f32_16x16x32_bf16 v[46:49], v[98:101], v[194:197], v[46:49]
	v_mfma_f32_16x16x32_bf16 v[42:45], v[106:109], v[194:197], v[42:45]
	v_mfma_f32_16x16x32_bf16 v[30:33], v[98:101], v[202:205], v[30:33]
	v_mfma_f32_16x16x32_bf16 v[26:29], v[106:109], v[202:205], v[26:29]
	v_mfma_f32_16x16x32_bf16 v[14:17], v[98:101], v[230:233], v[14:17]
	v_mfma_f32_16x16x32_bf16 v[10:13], v[106:109], v[230:233], v[10:13]
	v_mfma_f32_16x16x32_bf16 v[62:65], v[102:105], v[166:169], v[62:65]
	v_mfma_f32_16x16x32_bf16 v[58:61], v[110:113], v[166:169], v[58:61]
	v_mfma_f32_16x16x32_bf16 v[46:49], v[102:105], v[198:201], v[46:49]
	v_mfma_f32_16x16x32_bf16 v[42:45], v[110:113], v[198:201], v[42:45]
	v_mfma_f32_16x16x32_bf16 v[30:33], v[102:105], v[206:209], v[30:33]
	v_mfma_f32_16x16x32_bf16 v[26:29], v[110:113], v[206:209], v[26:29]
	v_mfma_f32_16x16x32_bf16 v[14:17], v[102:105], v[234:237], v[14:17]
	v_mfma_f32_16x16x32_bf16 v[10:13], v[110:113], v[234:237], v[10:13]
	s_setprio 0
	s_setprio 1
	v_mfma_f32_16x16x32_bf16 v[54:57], v[114:117], v[162:165], v[54:57]
	v_mfma_f32_16x16x32_bf16 v[50:53], v[122:125], v[162:165], v[50:53]
	v_mfma_f32_16x16x32_bf16 v[38:41], v[114:117], v[194:197], v[38:41]
	v_mfma_f32_16x16x32_bf16 v[34:37], v[122:125], v[194:197], v[34:37]
	v_mfma_f32_16x16x32_bf16 v[22:25], v[114:117], v[202:205], v[22:25]
	v_mfma_f32_16x16x32_bf16 v[18:21], v[122:125], v[202:205], v[18:21]
	v_mfma_f32_16x16x32_bf16 v[6:9], v[114:117], v[230:233], v[6:9]
	v_mfma_f32_16x16x32_bf16 v[2:5], v[122:125], v[230:233], v[2:5]
	v_mfma_f32_16x16x32_bf16 v[54:57], v[118:121], v[166:169], v[54:57]
	v_mfma_f32_16x16x32_bf16 v[50:53], v[126:129], v[166:169], v[50:53]
	v_mfma_f32_16x16x32_bf16 v[38:41], v[118:121], v[198:201], v[38:41]
	v_mfma_f32_16x16x32_bf16 v[34:37], v[126:129], v[198:201], v[34:37]
	v_mfma_f32_16x16x32_bf16 v[22:25], v[118:121], v[206:209], v[22:25]
	v_mfma_f32_16x16x32_bf16 v[18:21], v[126:129], v[206:209], v[18:21]
	v_mfma_f32_16x16x32_bf16 v[6:9], v[118:121], v[234:237], v[6:9]
	v_mfma_f32_16x16x32_bf16 v[2:5], v[126:129], v[234:237], v[2:5]
	s_setprio 0
	s_barrier
	s_add_i32 s62, 0, 0x18000
	s_add_i32 s63, 0, 0x1c000
	v_add_u32_e32 v110, s62, v227
	v_add_u32_e32 v126, s63, v227
	ds_read_b128 v[98:101], v110
	ds_read_b128 v[102:105], v110 offset:1024
	ds_read_b128 v[106:109], v110 offset:2048
	ds_read_b128 v[110:113], v110 offset:3072
	ds_read_b128 v[114:117], v126
	ds_read_b128 v[118:121], v126 offset:1024
	ds_read_b128 v[122:125], v126 offset:2048
	ds_read_b128 v[126:129], v126 offset:3072
	s_add_u32 s38, s38, 0x40000
	s_addc_u32 s39, s39, 0
	s_mov_b32 m0, s49
	v_lshl_add_u64 v[244:245], s[38:39], 0, v[188:189]
	ds_read_b128 v[162:165], v228 offset:32768
	ds_read_b128 v[166:169], v228 offset:33792
	ds_read_b128 v[194:197], v228 offset:34816
	ds_read_b128 v[198:201], v228 offset:35840
	ds_read_b128 v[202:205], v228 offset:36864
	ds_read_b128 v[206:209], v228 offset:37888
	ds_read_b128 v[230:233], v228 offset:38912
	ds_read_b128 v[234:237], v228 offset:39936
	global_load_lds_dwordx4 v[244:245], off
	v_lshl_add_u64 v[244:245], s[38:39], 0, v[186:187]
	s_mov_b32 m0, s50
	s_nop 0
	global_load_lds_dwordx4 v[244:245], off
	s_waitcnt vmcnt(8)
	s_waitcnt lgkmcnt(0)
	s_barrier
	s_setprio 1
	s_waitcnt lgkmcnt(0)
	v_mfma_f32_16x16x32_bf16 v[158:161], v[98:101], v[162:165], v[158:161]
	v_mfma_f32_16x16x32_bf16 v[154:157], v[106:109], v[162:165], v[154:157]
	v_mfma_f32_16x16x32_bf16 v[142:145], v[98:101], v[194:197], v[142:145]
	v_mfma_f32_16x16x32_bf16 v[138:141], v[106:109], v[194:197], v[138:141]
	v_mfma_f32_16x16x32_bf16 v[94:97], v[98:101], v[202:205], v[94:97]
	v_mfma_f32_16x16x32_bf16 v[90:93], v[106:109], v[202:205], v[90:93]
	v_mfma_f32_16x16x32_bf16 v[78:81], v[98:101], v[230:233], v[78:81]
	v_mfma_f32_16x16x32_bf16 v[74:77], v[106:109], v[230:233], v[74:77]
	v_mfma_f32_16x16x32_bf16 v[158:161], v[102:105], v[166:169], v[158:161]
	v_mfma_f32_16x16x32_bf16 v[154:157], v[110:113], v[166:169], v[154:157]
	v_mfma_f32_16x16x32_bf16 v[142:145], v[102:105], v[198:201], v[142:145]
	v_mfma_f32_16x16x32_bf16 v[138:141], v[110:113], v[198:201], v[138:141]
	v_mfma_f32_16x16x32_bf16 v[94:97], v[102:105], v[206:209], v[94:97]
	v_mfma_f32_16x16x32_bf16 v[90:93], v[110:113], v[206:209], v[90:93]
	v_mfma_f32_16x16x32_bf16 v[78:81], v[102:105], v[234:237], v[78:81]
	v_mfma_f32_16x16x32_bf16 v[74:77], v[110:113], v[234:237], v[74:77]
	s_setprio 0
	s_setprio 1
	v_mfma_f32_16x16x32_bf16 v[150:153], v[114:117], v[162:165], v[150:153]
	v_mfma_f32_16x16x32_bf16 v[146:149], v[122:125], v[162:165], v[146:149]
	v_mfma_f32_16x16x32_bf16 v[134:137], v[114:117], v[194:197], v[134:137]
	v_mfma_f32_16x16x32_bf16 v[130:133], v[122:125], v[194:197], v[130:133]
	v_mfma_f32_16x16x32_bf16 v[86:89], v[114:117], v[202:205], v[86:89]
	v_mfma_f32_16x16x32_bf16 v[82:85], v[122:125], v[202:205], v[82:85]
	v_mfma_f32_16x16x32_bf16 v[70:73], v[114:117], v[230:233], v[70:73]
	v_mfma_f32_16x16x32_bf16 v[66:69], v[122:125], v[230:233], v[66:69]
	v_mfma_f32_16x16x32_bf16 v[150:153], v[118:121], v[166:169], v[150:153]
	v_mfma_f32_16x16x32_bf16 v[146:149], v[126:129], v[166:169], v[146:149]
	v_mfma_f32_16x16x32_bf16 v[134:137], v[118:121], v[198:201], v[134:137]
	v_mfma_f32_16x16x32_bf16 v[130:133], v[126:129], v[198:201], v[130:133]
	v_mfma_f32_16x16x32_bf16 v[86:89], v[118:121], v[206:209], v[86:89]
	v_mfma_f32_16x16x32_bf16 v[82:85], v[126:129], v[206:209], v[82:85]
	v_mfma_f32_16x16x32_bf16 v[70:73], v[118:121], v[234:237], v[70:73]
	v_mfma_f32_16x16x32_bf16 v[66:69], v[126:129], v[234:237], v[66:69]
	s_setprio 0
	s_barrier
	s_add_i32 s38, s62, s46
	v_lshl_add_u64 v[210:211], v[210:211], 0, s[14:15]
	s_mov_b32 m0, s38
	ds_read_b128 v[162:165], v228 offset:49152
	ds_read_b128 v[166:169], v228 offset:50176
	ds_read_b128 v[194:197], v228 offset:51200
	ds_read_b128 v[198:201], v228 offset:52224
	ds_read_b128 v[202:205], v228 offset:53248
	ds_read_b128 v[206:209], v228 offset:54272
	ds_read_b128 v[230:233], v228 offset:55296
	ds_read_b128 v[234:237], v228 offset:56320
	global_load_lds_dwordx4 v[210:211], off
	s_add_i32 m0, s38, 0x2000
	s_add_u32 s24, s24, 0x40080
	v_lshl_add_u64 v[210:211], v[238:239], 0, s[14:15]
	s_addc_u32 s25, s25, 0
	s_add_i32 s38, s63, s46
	global_load_lds_dwordx4 v[210:211], off
	v_lshl_add_u64 v[210:211], s[24:25], 0, v[0:1]
	s_mov_b32 m0, s38
	s_nop 0
	global_load_lds_dwordx4 v[210:211], off
	v_lshl_add_u64 v[210:211], s[24:25], 0, v[184:185]
	s_add_i32 m0, s38, 0x2000
	s_nop 0
	global_load_lds_dwordx4 v[210:211], off
	v_lshl_add_u64 v[210:211], v[240:241], 0, s[14:15]
	s_mov_b32 m0, s54
	s_nop 0
	global_load_lds_dwordx4 v[210:211], off
	v_lshl_add_u64 v[210:211], v[242:243], 0, s[14:15]
	s_mov_b32 m0, s55
	s_nop 0
	global_load_lds_dwordx4 v[210:211], off
	s_waitcnt vmcnt(8)
	s_waitcnt lgkmcnt(0)
	s_barrier
	s_setprio 1
	s_waitcnt lgkmcnt(0)
	v_mfma_f32_16x16x32_bf16 v[62:65], v[98:101], v[162:165], v[62:65]
	v_mfma_f32_16x16x32_bf16 v[58:61], v[106:109], v[162:165], v[58:61]
	v_mfma_f32_16x16x32_bf16 v[46:49], v[98:101], v[194:197], v[46:49]
	v_mfma_f32_16x16x32_bf16 v[42:45], v[106:109], v[194:197], v[42:45]
	v_mfma_f32_16x16x32_bf16 v[30:33], v[98:101], v[202:205], v[30:33]
	v_mfma_f32_16x16x32_bf16 v[26:29], v[106:109], v[202:205], v[26:29]
	v_mfma_f32_16x16x32_bf16 v[14:17], v[98:101], v[230:233], v[14:17]
	v_mfma_f32_16x16x32_bf16 v[10:13], v[106:109], v[230:233], v[10:13]
	v_mfma_f32_16x16x32_bf16 v[62:65], v[102:105], v[166:169], v[62:65]
	v_mfma_f32_16x16x32_bf16 v[58:61], v[110:113], v[166:169], v[58:61]
	v_mfma_f32_16x16x32_bf16 v[46:49], v[102:105], v[198:201], v[46:49]
	v_mfma_f32_16x16x32_bf16 v[42:45], v[110:113], v[198:201], v[42:45]
	v_mfma_f32_16x16x32_bf16 v[30:33], v[102:105], v[206:209], v[30:33]
	v_mfma_f32_16x16x32_bf16 v[26:29], v[110:113], v[206:209], v[26:29]
	v_mfma_f32_16x16x32_bf16 v[14:17], v[102:105], v[234:237], v[14:17]
	v_mfma_f32_16x16x32_bf16 v[10:13], v[110:113], v[234:237], v[10:13]
	s_setprio 0
	s_setprio 1
	v_mfma_f32_16x16x32_bf16 v[54:57], v[114:117], v[162:165], v[54:57]
	v_mfma_f32_16x16x32_bf16 v[50:53], v[122:125], v[162:165], v[50:53]
	v_mfma_f32_16x16x32_bf16 v[38:41], v[114:117], v[194:197], v[38:41]
	v_mfma_f32_16x16x32_bf16 v[34:37], v[122:125], v[194:197], v[34:37]
	v_mfma_f32_16x16x32_bf16 v[22:25], v[114:117], v[202:205], v[22:25]
	v_mfma_f32_16x16x32_bf16 v[18:21], v[122:125], v[202:205], v[18:21]
	v_mfma_f32_16x16x32_bf16 v[6:9], v[114:117], v[230:233], v[6:9]
	v_mfma_f32_16x16x32_bf16 v[2:5], v[122:125], v[230:233], v[2:5]
	v_mfma_f32_16x16x32_bf16 v[54:57], v[118:121], v[166:169], v[54:57]
	v_mfma_f32_16x16x32_bf16 v[50:53], v[126:129], v[166:169], v[50:53]
	v_mfma_f32_16x16x32_bf16 v[38:41], v[118:121], v[198:201], v[38:41]
	v_mfma_f32_16x16x32_bf16 v[34:37], v[126:129], v[198:201], v[34:37]
	v_mfma_f32_16x16x32_bf16 v[22:25], v[118:121], v[206:209], v[22:25]
	v_mfma_f32_16x16x32_bf16 v[18:21], v[126:129], v[206:209], v[18:21]
	v_mfma_f32_16x16x32_bf16 v[6:9], v[118:121], v[234:237], v[6:9]
	v_mfma_f32_16x16x32_bf16 v[2:5], v[126:129], v[234:237], v[2:5]
	s_setprio 0
	s_barrier
	s_add_i32 s61, s61, 2
	s_add_u32 s22, s22, 0x100
	s_addc_u32 s23, s23, 0
	s_add_u32 s42, s42, 0x100
	s_addc_u32 s43, s43, 0
	s_cmp_gt_u32 s61, 13
	s_cbranch_scc0 .LBB0_304
	s_and_b64 vcc, exec, s[10:11]
	s_cbranch_vccz .LBB0_307
	s_barrier
.LBB0_307:
	s_lshl_b32 s13, s34, 8
	v_mov_b32_e32 v229, v226
	v_mov_b32_e32 v98, v183
	s_add_i32 s13, s13, s53
	s_lshl_b32 s22, s60, 8
	v_add_u32_e32 v198, s13, v98
	v_lshlrev_b32_e32 v196, 3, v229
	v_add_u32_e32 v204, 16, v198
	v_add_u32_e32 v202, 32, v198
	v_add_u32_e32 v200, 48, v198
	v_ashrrev_i32_e32 v197, 31, v196
	s_ashr_i32 s23, s22, 31
	s_mov_b64 s[24:25], -1
	s_and_b64 vcc, exec, s[4:5]
	v_ashrrev_i32_e32 v199, 31, v198
	v_ashrrev_i32_e32 v205, 31, v204
	v_ashrrev_i32_e32 v203, 31, v202
	v_ashrrev_i32_e32 v201, 31, v200
	s_cbranch_vccz .LBB0_309
	s_lshl_b64 s[24:25], s[22:23], 1
	s_add_u32 s24, s57, s24
	s_addc_u32 s25, s58, s25
	v_lshl_add_u64 v[122:123], v[196:197], 1, s[24:25]
	v_lshlrev_b64 v[98:99], 11, v[198:199]
	v_lshlrev_b64 v[106:107], 11, v[204:205]
	v_lshlrev_b64 v[114:115], 11, v[202:203]
	v_lshlrev_b64 v[124:125], 11, v[200:201]
	v_lshl_add_u64 v[102:103], v[122:123], 0, v[98:99]
	v_lshl_add_u64 v[110:111], v[122:123], 0, v[106:107]
	v_lshl_add_u64 v[118:119], v[122:123], 0, v[114:115]
	v_lshl_add_u64 v[126:127], v[122:123], 0, v[124:125]
	v_mov_b32_e32 v98, 0
	v_mov_b32_e32 v99, 0
	v_mov_b32_e32 v100, 0
	v_mov_b32_e32 v101, 0
	s_nop 0
	v_mov_b32_e32 v102, 0
	v_mov_b32_e32 v103, 0
	v_mov_b32_e32 v104, 0
	v_mov_b32_e32 v105, 0
	s_nop 0
	v_mov_b32_e32 v106, 0
	v_mov_b32_e32 v107, 0
	v_mov_b32_e32 v108, 0
	v_mov_b32_e32 v109, 0
	s_nop 0
	v_mov_b32_e32 v110, 0
	v_mov_b32_e32 v111, 0
	v_mov_b32_e32 v112, 0
	v_mov_b32_e32 v113, 0
	s_nop 0
	v_mov_b32_e32 v114, 0
	v_mov_b32_e32 v115, 0
	v_mov_b32_e32 v116, 0
	v_mov_b32_e32 v117, 0
	s_nop 0
	v_mov_b32_e32 v118, 0
	v_mov_b32_e32 v119, 0
	v_mov_b32_e32 v120, 0
	v_mov_b32_e32 v121, 0
	s_nop 0
	v_mov_b32_e32 v122, 0
	v_mov_b32_e32 v123, 0
	v_mov_b32_e32 v124, 0
	v_mov_b32_e32 v125, 0
	s_nop 0
	v_mov_b32_e32 v126, 0
	v_mov_b32_e32 v127, 0
	v_mov_b32_e32 v128, 0
	v_mov_b32_e32 v129, 0
	s_mov_b64 s[24:25], 0

.LBB0_313:
	v_lshl_add_u64 v[194:195], v[196:197], 0, s[8:9]
	v_lshlrev_b64 v[206:207], 10, v[198:199]
	v_lshl_add_u64 v[206:207], v[206:207], 0, v[194:195]
	v_lshl_add_u64 v[210:211], v[206:207], 0, s[22:23]
	s_andn2_b64 vcc, exec, s[24:25]
	v_lshl_add_u64 v[208:209], v[210:211], 2, s[72:73]
	s_cbranch_vccnz .LBB0_315
	global_load_dwordx4 v[162:165], v[208:209], off offset:16
	global_load_dwordx4 v[166:169], v[208:209], off
	s_waitcnt vmcnt(0)
.LBB0_315:
	v_pk_add_f32 v[160:161], v[160:161], v[168:169]
	v_pk_add_f32 v[158:159], v[158:159], v[166:167]
	v_pk_add_f32 v[156:157], v[156:157], v[164:165]
	v_pk_add_f32 v[154:155], v[154:155], v[162:163]
	s_mov_b64 s[24:25], -1
	s_and_b64 vcc, exec, s[6:7]
	s_cbranch_vccz .LBB0_317
	v_pk_mul_f32 v[162:163], v[160:161], v[160:161]
	v_pk_mul_f32 v[164:165], v[158:159], v[158:159]
	s_nop 0
	v_pk_mov_b32 v[166:167], v[164:165], v[162:163] op_sel:[1,0]
	v_mov_b32_e32 v165, v163
	v_pk_add_f32 v[162:163], v[166:167], v[164:165]
	v_pk_mul_f32 v[164:165], v[156:157], v[156:157]
	v_pk_mul_f32 v[166:167], v[154:155], v[154:155]
	v_mov_b32_e32 v168, v164
	v_mov_b32_e32 v169, v166
	v_mov_b32_e32 v166, v165
	v_pk_add_f32 v[164:165], v[168:169], v[166:167]
	v_add_f32_e32 v162, v162, v163
	v_add_f32_e32 v162, v162, v165
	v_add_f32_e32 v164, v164, v162
	v_lshl_add_u64 v[162:163], v[210:211], 1, s[28:29]
	v_cvt_pk_bf16_f32 v166, v158, v159
	v_cvt_pk_bf16_f32 v167, v160, v161
	v_cvt_pk_bf16_f32 v168, v154, v155
	v_cvt_pk_bf16_f32 v169, v156, v157
	global_store_dwordx4 v[162:163], v[166:169], off
	v_lshl_add_u64 v[162:163], v[210:211], 2, s[90:91]
	s_cbranch_execnz .LBB0_319
	s_branch .LBB0_318

.LBB0_322:
	global_load_dwordx4 v[154:157], v[208:209], off offset:528
	global_load_dwordx4 v[158:161], v[208:209], off offset:512
	s_waitcnt vmcnt(0)
.LBB0_323:
	s_or_b32 s24, s22, 0x80
	s_mov_b32 s25, s23
	v_pk_add_f32 v[152:153], v[152:153], v[160:161]
	v_pk_add_f32 v[150:151], v[150:151], v[158:159]
	v_pk_add_f32 v[148:149], v[148:149], v[156:157]
	v_pk_add_f32 v[146:147], v[146:147], v[154:155]
	s_mov_b64 s[38:39], -1
	s_and_b64 vcc, exec, s[6:7]
	s_cbranch_vccz .LBB0_325
	v_pk_mul_f32 v[154:155], v[152:153], v[152:153]
	v_pk_mul_f32 v[158:159], v[150:151], v[150:151]
	v_lshl_add_u64 v[156:157], v[206:207], 0, s[24:25]
	v_pk_mov_b32 v[160:161], v[158:159], v[154:155] op_sel:[1,0]
	v_mov_b32_e32 v159, v155
	v_pk_add_f32 v[154:155], v[160:161], v[158:159]
	v_pk_mul_f32 v[158:159], v[148:149], v[148:149]
	v_pk_mul_f32 v[160:161], v[146:147], v[146:147]
	v_mov_b32_e32 v166, v158
	v_mov_b32_e32 v167, v160
	v_mov_b32_e32 v160, v159
	v_pk_add_f32 v[158:159], v[166:167], v[160:161]
	v_add_f32_e32 v154, v154, v155
	v_add_f32_e32 v154, v154, v159
	v_add_f32_e32 v154, v158, v154
	v_lshl_add_u64 v[160:161], v[156:157], 1, s[28:29]
	v_cvt_pk_bf16_f32 v156, v150, v151
	v_cvt_pk_bf16_f32 v157, v152, v153
	v_cvt_pk_bf16_f32 v158, v146, v147
	v_cvt_pk_bf16_f32 v159, v148, v149
	v_add_f32_e32 v154, v164, v154
	global_store_dwordx4 v[160:161], v[156:159], off
	s_mov_b64 s[38:39], 0

.LBB0_333:
	v_lshlrev_b64 v[154:155], 10, v[204:205]
	v_lshl_add_u64 v[154:155], v[154:155], 0, v[194:195]
	v_lshl_add_u64 v[158:159], v[154:155], 0, s[22:23]
	s_andn2_b64 vcc, exec, s[42:43]
	v_lshl_add_u64 v[156:157], v[158:159], 2, s[72:73]
	s_cbranch_vccnz .LBB0_335
	s_waitcnt lgkmcnt(0)
	global_load_dwordx4 v[146:149], v[156:157], off offset:16
	global_load_dwordx4 v[150:153], v[156:157], off
	s_waitcnt vmcnt(0)
.LBB0_335:
	v_pk_add_f32 v[144:145], v[144:145], v[152:153]
	v_pk_add_f32 v[142:143], v[142:143], v[150:151]
	v_pk_add_f32 v[140:141], v[140:141], v[148:149]
	s_waitcnt lgkmcnt(0)
	v_pk_add_f32 v[138:139], v[138:139], v[146:147]
	s_mov_b64 s[42:43], -1
	s_and_b64 vcc, exec, s[6:7]
	s_cbranch_vccz .LBB0_337
	v_pk_mul_f32 v[146:147], v[144:145], v[144:145]
	v_pk_mul_f32 v[148:149], v[142:143], v[142:143]
	s_nop 0
	v_pk_mov_b32 v[150:151], v[148:149], v[146:147] op_sel:[1,0]
	v_mov_b32_e32 v149, v147
	v_pk_add_f32 v[146:147], v[150:151], v[148:149]
	v_pk_mul_f32 v[148:149], v[140:141], v[140:141]
	v_pk_mul_f32 v[150:151], v[138:139], v[138:139]
	v_mov_b32_e32 v152, v148
	v_mov_b32_e32 v153, v150
	v_mov_b32_e32 v150, v149
	v_pk_add_f32 v[148:149], v[152:153], v[150:151]
	v_add_f32_e32 v146, v146, v147
	v_add_f32_e32 v146, v146, v149
	v_add_f32_e32 v148, v148, v146
	v_lshl_add_u64 v[146:147], v[158:159], 1, s[28:29]
	v_cvt_pk_bf16_f32 v150, v142, v143
	v_cvt_pk_bf16_f32 v151, v144, v145
	v_cvt_pk_bf16_f32 v152, v138, v139
	v_cvt_pk_bf16_f32 v153, v140, v141
	global_store_dwordx4 v[146:147], v[150:153], off
	v_lshl_add_u64 v[146:147], v[158:159], 2, s[90:91]
	s_cbranch_execnz .LBB0_339
	s_branch .LBB0_338

.LBB0_342:
	global_load_dwordx4 v[138:141], v[156:157], off offset:528
	global_load_dwordx4 v[142:145], v[156:157], off offset:512
	s_waitcnt vmcnt(0)
.LBB0_343:
	v_pk_add_f32 v[136:137], v[136:137], v[144:145]
	v_pk_add_f32 v[134:135], v[134:135], v[142:143]
	v_pk_add_f32 v[132:133], v[132:133], v[140:141]
	v_pk_add_f32 v[130:131], v[130:131], v[138:139]
	s_mov_b64 s[42:43], -1
	s_and_b64 vcc, exec, s[6:7]
	s_cbranch_vccz .LBB0_352
	v_pk_mul_f32 v[138:139], v[136:137], v[136:137]
	v_pk_mul_f32 v[142:143], v[134:135], v[134:135]
	v_lshl_add_u64 v[140:141], v[154:155], 0, s[24:25]
	v_pk_mov_b32 v[144:145], v[142:143], v[138:139] op_sel:[1,0]
	v_mov_b32_e32 v143, v139
	v_pk_add_f32 v[138:139], v[144:145], v[142:143]
	v_pk_mul_f32 v[142:143], v[132:133], v[132:133]
	v_pk_mul_f32 v[144:145], v[130:131], v[130:131]
	v_mov_b32_e32 v150, v142
	v_mov_b32_e32 v151, v144
	v_mov_b32_e32 v144, v143
	v_pk_add_f32 v[142:143], v[150:151], v[144:145]
	v_add_f32_e32 v138, v138, v139
	v_add_f32_e32 v138, v138, v143
	v_add_f32_e32 v138, v142, v138
	v_lshl_add_u64 v[144:145], v[140:141], 1, s[28:29]
	v_cvt_pk_bf16_f32 v140, v134, v135
	v_cvt_pk_bf16_f32 v141, v136, v137
	v_cvt_pk_bf16_f32 v142, v130, v131
	v_cvt_pk_bf16_f32 v143, v132, v133
	v_add_f32_e32 v138, v148, v138
	global_store_dwordx4 v[144:145], v[140:143], off
	s_cbranch_execz .LBB0_353

.LBB0_348:
	v_lshlrev_b64 v[138:139], 10, v[202:203]
	v_lshl_add_u64 v[138:139], v[138:139], 0, v[194:195]
	v_lshl_add_u64 v[142:143], v[138:139], 0, s[22:23]
	s_andn2_b64 vcc, exec, s[42:43]
	v_lshl_add_u64 v[140:141], v[142:143], 2, s[72:73]
	s_cbranch_vccnz .LBB0_350
	s_waitcnt lgkmcnt(0)
	global_load_dwordx4 v[130:133], v[140:141], off offset:16
	global_load_dwordx4 v[134:137], v[140:141], off
	s_waitcnt vmcnt(0)
.LBB0_350:
	v_pk_add_f32 v[96:97], v[96:97], v[136:137]
	v_pk_add_f32 v[94:95], v[94:95], v[134:135]
	v_pk_add_f32 v[92:93], v[92:93], v[132:133]
	s_waitcnt lgkmcnt(0)
	v_pk_add_f32 v[90:91], v[90:91], v[130:131]
	s_mov_b64 s[42:43], -1
	s_and_b64 vcc, exec, s[6:7]
	s_cbranch_vccz .LBB0_357
	v_pk_mul_f32 v[130:131], v[96:97], v[96:97]
	v_pk_mul_f32 v[132:133], v[94:95], v[94:95]
	s_nop 0
	v_pk_mov_b32 v[134:135], v[132:133], v[130:131] op_sel:[1,0]
	v_mov_b32_e32 v133, v131
	v_pk_add_f32 v[130:131], v[134:135], v[132:133]
	v_pk_mul_f32 v[132:133], v[92:93], v[92:93]
	v_pk_mul_f32 v[134:135], v[90:91], v[90:91]
	v_mov_b32_e32 v136, v132
	v_mov_b32_e32 v137, v134
	v_mov_b32_e32 v134, v133
	v_pk_add_f32 v[132:133], v[136:137], v[134:135]
	v_add_f32_e32 v130, v130, v131
	v_add_f32_e32 v130, v130, v133
	v_add_f32_e32 v132, v132, v130
	v_lshl_add_u64 v[130:131], v[142:143], 1, s[28:29]
	v_cvt_pk_bf16_f32 v134, v94, v95
	v_cvt_pk_bf16_f32 v135, v96, v97
	v_cvt_pk_bf16_f32 v136, v90, v91
	v_cvt_pk_bf16_f32 v137, v92, v93
	global_store_dwordx4 v[130:131], v[134:137], off
	v_lshl_add_u64 v[130:131], v[142:143], 2, s[90:91]
	s_cbranch_execnz .LBB0_359
	s_branch .LBB0_358

.LBB0_362:
	global_load_dwordx4 v[90:93], v[140:141], off offset:528
	global_load_dwordx4 v[94:97], v[140:141], off offset:512
	s_waitcnt vmcnt(0)
.LBB0_363:
	v_pk_add_f32 v[88:89], v[88:89], v[96:97]
	v_pk_add_f32 v[86:87], v[86:87], v[94:95]
	v_pk_add_f32 v[84:85], v[84:85], v[92:93]
	v_pk_add_f32 v[82:83], v[82:83], v[90:91]
	s_mov_b64 s[42:43], -1
	s_and_b64 vcc, exec, s[6:7]
	s_cbranch_vccz .LBB0_372
	v_pk_mul_f32 v[90:91], v[88:89], v[88:89]
	v_pk_mul_f32 v[94:95], v[86:87], v[86:87]
	v_lshl_add_u64 v[92:93], v[138:139], 0, s[24:25]
	v_pk_mov_b32 v[96:97], v[94:95], v[90:91] op_sel:[1,0]
	v_mov_b32_e32 v95, v91
	v_pk_add_f32 v[90:91], v[96:97], v[94:95]
	v_pk_mul_f32 v[94:95], v[84:85], v[84:85]
	v_pk_mul_f32 v[96:97], v[82:83], v[82:83]
	v_mov_b32_e32 v134, v94
	v_mov_b32_e32 v135, v96
	v_mov_b32_e32 v96, v95
	v_pk_add_f32 v[94:95], v[134:135], v[96:97]
	v_add_f32_e32 v90, v90, v91
	v_add_f32_e32 v90, v90, v95
	v_add_f32_e32 v90, v94, v90
	v_lshl_add_u64 v[96:97], v[92:93], 1, s[28:29]
	v_cvt_pk_bf16_f32 v92, v86, v87
	v_cvt_pk_bf16_f32 v93, v88, v89
	v_cvt_pk_bf16_f32 v94, v82, v83
	v_cvt_pk_bf16_f32 v95, v84, v85
	v_add_f32_e32 v90, v132, v90
	global_store_dwordx4 v[96:97], v[92:95], off
	s_cbranch_execz .LBB0_373

.LBB0_368:
	v_lshlrev_b64 v[90:91], 10, v[200:201]
	v_lshl_add_u64 v[90:91], v[90:91], 0, v[194:195]
	v_lshl_add_u64 v[94:95], v[90:91], 0, s[22:23]
	s_andn2_b64 vcc, exec, s[42:43]
	v_lshl_add_u64 v[92:93], v[94:95], 2, s[72:73]
	s_cbranch_vccnz .LBB0_370
	s_waitcnt lgkmcnt(0)
	global_load_dwordx4 v[82:85], v[92:93], off offset:16
	global_load_dwordx4 v[86:89], v[92:93], off
	s_waitcnt vmcnt(0)
.LBB0_370:
	v_pk_add_f32 v[80:81], v[80:81], v[88:89]
	v_pk_add_f32 v[78:79], v[78:79], v[86:87]
	v_pk_add_f32 v[76:77], v[76:77], v[84:85]
	s_waitcnt lgkmcnt(0)
	v_pk_add_f32 v[74:75], v[74:75], v[82:83]
	s_mov_b64 s[42:43], -1
	s_and_b64 vcc, exec, s[6:7]
	s_cbranch_vccz .LBB0_377
	v_pk_mul_f32 v[82:83], v[80:81], v[80:81]
	v_pk_mul_f32 v[84:85], v[78:79], v[78:79]
	s_nop 0
	v_pk_mov_b32 v[86:87], v[84:85], v[82:83] op_sel:[1,0]
	v_mov_b32_e32 v85, v83
	v_pk_add_f32 v[82:83], v[86:87], v[84:85]
	v_pk_mul_f32 v[84:85], v[76:77], v[76:77]
	v_pk_mul_f32 v[86:87], v[74:75], v[74:75]
	v_mov_b32_e32 v88, v84
	v_mov_b32_e32 v89, v86
	v_mov_b32_e32 v86, v85
	v_pk_add_f32 v[84:85], v[88:89], v[86:87]
	v_add_f32_e32 v82, v82, v83
	v_add_f32_e32 v82, v82, v85
	v_add_f32_e32 v84, v84, v82
	v_lshl_add_u64 v[82:83], v[94:95], 1, s[28:29]
	v_cvt_pk_bf16_f32 v86, v78, v79
	v_cvt_pk_bf16_f32 v87, v80, v81
	v_cvt_pk_bf16_f32 v88, v74, v75
	v_cvt_pk_bf16_f32 v89, v76, v77
	global_store_dwordx4 v[82:83], v[86:89], off
	v_lshl_add_u64 v[82:83], v[94:95], 2, s[90:91]
	s_cbranch_execnz .LBB0_379
	s_branch .LBB0_378

.LBB0_382:
	global_load_dwordx4 v[74:77], v[92:93], off offset:528
	global_load_dwordx4 v[78:81], v[92:93], off offset:512
	s_waitcnt vmcnt(0)
.LBB0_383:
	v_pk_add_f32 v[72:73], v[72:73], v[80:81]
	v_pk_add_f32 v[70:71], v[70:71], v[78:79]
	v_pk_add_f32 v[68:69], v[68:69], v[76:77]
	v_pk_add_f32 v[66:67], v[66:67], v[74:75]
	s_mov_b64 s[42:43], -1
	s_and_b64 vcc, exec, s[6:7]
	s_cbranch_vccz .LBB0_386
	v_pk_mul_f32 v[74:75], v[72:73], v[72:73]
	v_pk_mul_f32 v[78:79], v[70:71], v[70:71]
	v_lshl_add_u64 v[76:77], v[90:91], 0, s[24:25]
	v_pk_mov_b32 v[80:81], v[78:79], v[74:75] op_sel:[1,0]
	v_mov_b32_e32 v79, v75
	v_pk_add_f32 v[74:75], v[80:81], v[78:79]
	v_pk_mul_f32 v[78:79], v[68:69], v[68:69]
	v_pk_mul_f32 v[80:81], v[66:67], v[66:67]
	v_mov_b32_e32 v86, v78
	v_mov_b32_e32 v87, v80
	v_mov_b32_e32 v80, v79
	v_pk_add_f32 v[78:79], v[86:87], v[80:81]
	v_add_f32_e32 v74, v74, v75
	v_add_f32_e32 v74, v74, v79
	v_add_f32_e32 v74, v78, v74
	v_lshl_add_u64 v[80:81], v[76:77], 1, s[28:29]
	v_cvt_pk_bf16_f32 v76, v70, v71
	v_cvt_pk_bf16_f32 v77, v72, v73
	v_cvt_pk_bf16_f32 v78, v66, v67
	v_cvt_pk_bf16_f32 v79, v68, v69
	v_add_f32_e32 v74, v84, v74
	global_store_dwordx4 v[80:81], v[76:79], off
	s_cbranch_execz .LBB0_387

.LBB0_391:
	v_add_u32_e32 v136, 0x80, v198
	v_add_u32_e32 v134, 0x90, v198
	v_add_u32_e32 v132, 0xa0, v198
	v_add_u32_e32 v130, 0xb0, v198
	s_mov_b64 s[42:43], -1
	s_and_b64 vcc, exec, s[4:5]
	v_ashrrev_i32_e32 v137, 31, v136
	v_ashrrev_i32_e32 v135, 31, v134
	v_ashrrev_i32_e32 v133, 31, v132
	v_ashrrev_i32_e32 v131, 31, v130
	s_cbranch_vccz .LBB0_393
	s_lshl_b64 s[42:43], s[22:23], 1
	s_add_u32 s42, s57, s42
	s_addc_u32 s43, s58, s43
	s_waitcnt lgkmcnt(0)
	v_lshl_add_u64 v[66:67], v[196:197], 1, s[42:43]
	v_lshlrev_b64 v[68:69], 11, v[136:137]
	v_lshl_add_u64 v[68:69], v[66:67], 0, v[68:69]
	v_mov_b32_e32 v94, 0
	v_mov_b32_e32 v95, 0
	v_mov_b32_e32 v96, 0
	v_mov_b32_e32 v97, 0
	v_mov_b32_e32 v90, 0
	v_mov_b32_e32 v91, 0
	v_mov_b32_e32 v92, 0
	v_mov_b32_e32 v93, 0
	v_lshlrev_b64 v[68:69], 11, v[134:135]
	v_lshl_add_u64 v[68:69], v[66:67], 0, v[68:69]
	v_mov_b32_e32 v86, 0
	v_mov_b32_e32 v87, 0
	v_mov_b32_e32 v88, 0
	v_mov_b32_e32 v89, 0
	v_mov_b32_e32 v82, 0
	v_mov_b32_e32 v83, 0
	v_mov_b32_e32 v84, 0
	v_mov_b32_e32 v85, 0
	v_lshlrev_b64 v[68:69], 11, v[132:133]
	v_lshl_add_u64 v[68:69], v[66:67], 0, v[68:69]
	v_mov_b32_e32 v78, 0
	v_mov_b32_e32 v79, 0
	v_mov_b32_e32 v80, 0
	v_mov_b32_e32 v81, 0
	v_mov_b32_e32 v74, 0
	v_mov_b32_e32 v75, 0
	v_mov_b32_e32 v76, 0
	v_mov_b32_e32 v77, 0
	v_lshlrev_b64 v[68:69], 11, v[130:131]
	v_lshl_add_u64 v[66:67], v[66:67], 0, v[68:69]
	v_mov_b32_e32 v70, 0
	v_mov_b32_e32 v71, 0
	v_mov_b32_e32 v72, 0
	v_mov_b32_e32 v73, 0
	s_nop 0
	v_mov_b32_e32 v66, 0
	v_mov_b32_e32 v67, 0
	v_mov_b32_e32 v68, 0
	v_mov_b32_e32 v69, 0
	s_cbranch_execnz .LBB0_395
	s_branch .LBB0_394

.LBB0_397:
	v_lshlrev_b64 v[94:95], 10, v[136:137]
	v_lshl_add_u64 v[94:95], v[94:95], 0, v[194:195]
	v_lshl_add_u64 v[96:97], v[94:95], 0, s[22:23]
	s_andn2_b64 vcc, exec, s[42:43]
	v_lshl_add_u64 v[106:107], v[96:97], 2, s[72:73]
	s_cbranch_vccnz .LBB0_399
	global_load_dwordx4 v[98:101], v[106:107], off offset:16
	global_load_dwordx4 v[102:105], v[106:107], off
	s_waitcnt vmcnt(0)
.LBB0_399:
	v_pk_add_f32 v[64:65], v[64:65], v[104:105]
	v_pk_add_f32 v[62:63], v[62:63], v[102:103]
	v_pk_add_f32 v[60:61], v[60:61], v[100:101]
	v_pk_add_f32 v[58:59], v[58:59], v[98:99]
	s_mov_b64 s[42:43], -1
	s_and_b64 vcc, exec, s[6:7]
	s_cbranch_vccz .LBB0_401
	v_pk_mul_f32 v[98:99], v[64:65], v[64:65]
	v_pk_mul_f32 v[100:101], v[62:63], v[62:63]
	s_nop 0
	v_pk_mov_b32 v[102:103], v[100:101], v[98:99] op_sel:[1,0]
	v_mov_b32_e32 v101, v99
	v_pk_add_f32 v[98:99], v[102:103], v[100:101]
	v_pk_mul_f32 v[100:101], v[60:61], v[60:61]
	v_pk_mul_f32 v[102:103], v[58:59], v[58:59]
	v_mov_b32_e32 v104, v100
	v_mov_b32_e32 v105, v102
	v_mov_b32_e32 v102, v101
	v_pk_add_f32 v[100:101], v[104:105], v[102:103]
	v_add_f32_e32 v98, v98, v99
	v_add_f32_e32 v98, v98, v101
	v_add_f32_e32 v98, v100, v98
	v_lshl_add_u64 v[104:105], v[96:97], 1, s[28:29]
	v_cvt_pk_bf16_f32 v100, v62, v63
	v_cvt_pk_bf16_f32 v101, v64, v65
	v_cvt_pk_bf16_f32 v102, v58, v59
	v_cvt_pk_bf16_f32 v103, v60, v61
	global_store_dwordx4 v[104:105], v[100:103], off
	v_lshl_add_u64 v[96:97], v[96:97], 2, s[90:91]
	s_cbranch_execnz .LBB0_403
	s_branch .LBB0_402

.LBB0_406:
	global_load_dwordx4 v[58:61], v[106:107], off offset:528
	global_load_dwordx4 v[62:65], v[106:107], off offset:512
	s_waitcnt vmcnt(0)
.LBB0_407:
	v_pk_add_f32 v[56:57], v[56:57], v[64:65]
	v_pk_add_f32 v[54:55], v[54:55], v[62:63]
	v_pk_add_f32 v[52:53], v[52:53], v[60:61]
	v_pk_add_f32 v[50:51], v[50:51], v[58:59]
	s_mov_b64 s[42:43], -1
	s_and_b64 vcc, exec, s[6:7]
	s_cbranch_vccz .LBB0_416
	v_pk_mul_f32 v[58:59], v[56:57], v[56:57]
	v_pk_mul_f32 v[62:63], v[54:55], v[54:55]
	v_lshl_add_u64 v[60:61], v[94:95], 0, s[24:25]
	v_pk_mov_b32 v[64:65], v[62:63], v[58:59] op_sel:[1,0]
	v_mov_b32_e32 v63, v59
	v_pk_add_f32 v[58:59], v[64:65], v[62:63]
	v_pk_mul_f32 v[62:63], v[52:53], v[52:53]
	v_pk_mul_f32 v[64:65], v[50:51], v[50:51]
	v_mov_b32_e32 v90, v62
	v_mov_b32_e32 v91, v64
	v_mov_b32_e32 v64, v63
	v_pk_add_f32 v[62:63], v[90:91], v[64:65]
	v_add_f32_e32 v58, v58, v59
	v_add_f32_e32 v58, v58, v63
	v_add_f32_e32 v58, v62, v58
	v_lshl_add_u64 v[64:65], v[60:61], 1, s[28:29]
	v_cvt_pk_bf16_f32 v60, v54, v55
	v_cvt_pk_bf16_f32 v61, v56, v57
	v_cvt_pk_bf16_f32 v62, v50, v51
	v_cvt_pk_bf16_f32 v63, v52, v53
	v_add_f32_e32 v58, v98, v58
	global_store_dwordx4 v[64:65], v[60:63], off
	s_cbranch_execz .LBB0_417

.LBB0_412:
	v_lshlrev_b64 v[58:59], 10, v[134:135]
	v_lshl_add_u64 v[58:59], v[58:59], 0, v[194:195]
	v_lshl_add_u64 v[62:63], v[58:59], 0, s[22:23]
	s_andn2_b64 vcc, exec, s[42:43]
	v_lshl_add_u64 v[60:61], v[62:63], 2, s[72:73]
	s_cbranch_vccnz .LBB0_414
	s_waitcnt lgkmcnt(0)
	global_load_dwordx4 v[50:53], v[60:61], off offset:16
	global_load_dwordx4 v[54:57], v[60:61], off
	s_waitcnt vmcnt(0)
.LBB0_414:
	v_pk_add_f32 v[48:49], v[48:49], v[56:57]
	v_pk_add_f32 v[46:47], v[46:47], v[54:55]
	v_pk_add_f32 v[44:45], v[44:45], v[52:53]
	s_waitcnt lgkmcnt(0)
	v_pk_add_f32 v[42:43], v[42:43], v[50:51]
	s_mov_b64 s[42:43], -1
	s_and_b64 vcc, exec, s[6:7]
	s_cbranch_vccz .LBB0_421
	v_pk_mul_f32 v[50:51], v[48:49], v[48:49]
	v_pk_mul_f32 v[52:53], v[46:47], v[46:47]
	s_nop 0
	v_pk_mov_b32 v[54:55], v[52:53], v[50:51] op_sel:[1,0]
	v_mov_b32_e32 v53, v51
	v_pk_add_f32 v[50:51], v[54:55], v[52:53]
	v_pk_mul_f32 v[52:53], v[44:45], v[44:45]
	v_pk_mul_f32 v[54:55], v[42:43], v[42:43]
	v_mov_b32_e32 v56, v52
	v_mov_b32_e32 v57, v54
	v_mov_b32_e32 v54, v53
	v_pk_add_f32 v[52:53], v[56:57], v[54:55]
	v_add_f32_e32 v50, v50, v51
	v_add_f32_e32 v50, v50, v53
	v_add_f32_e32 v52, v52, v50
	v_lshl_add_u64 v[50:51], v[62:63], 1, s[28:29]
	v_cvt_pk_bf16_f32 v54, v46, v47
	v_cvt_pk_bf16_f32 v55, v48, v49
	v_cvt_pk_bf16_f32 v56, v42, v43
	v_cvt_pk_bf16_f32 v57, v44, v45
	global_store_dwordx4 v[50:51], v[54:57], off
	v_lshl_add_u64 v[50:51], v[62:63], 2, s[90:91]
	s_cbranch_execnz .LBB0_423
	s_branch .LBB0_422

.LBB0_426:
	global_load_dwordx4 v[42:45], v[60:61], off offset:528
	global_load_dwordx4 v[46:49], v[60:61], off offset:512
	s_waitcnt vmcnt(0)
.LBB0_427:
	v_pk_add_f32 v[40:41], v[40:41], v[48:49]
	v_pk_add_f32 v[38:39], v[38:39], v[46:47]
	v_pk_add_f32 v[36:37], v[36:37], v[44:45]
	v_pk_add_f32 v[34:35], v[34:35], v[42:43]
	s_mov_b64 s[42:43], -1
	s_and_b64 vcc, exec, s[6:7]
	s_cbranch_vccz .LBB0_436
	v_pk_mul_f32 v[42:43], v[40:41], v[40:41]
	v_pk_mul_f32 v[46:47], v[38:39], v[38:39]
	v_lshl_add_u64 v[44:45], v[58:59], 0, s[24:25]
	v_pk_mov_b32 v[48:49], v[46:47], v[42:43] op_sel:[1,0]
	v_mov_b32_e32 v47, v43
	v_pk_add_f32 v[42:43], v[48:49], v[46:47]
	v_pk_mul_f32 v[46:47], v[36:37], v[36:37]
	v_pk_mul_f32 v[48:49], v[34:35], v[34:35]
	v_mov_b32_e32 v54, v46
	v_mov_b32_e32 v55, v48
	v_mov_b32_e32 v48, v47
	v_pk_add_f32 v[46:47], v[54:55], v[48:49]
	v_add_f32_e32 v42, v42, v43
	v_add_f32_e32 v42, v42, v47
	v_add_f32_e32 v42, v46, v42
	v_lshl_add_u64 v[48:49], v[44:45], 1, s[28:29]
	v_cvt_pk_bf16_f32 v44, v38, v39
	v_cvt_pk_bf16_f32 v45, v40, v41
	v_cvt_pk_bf16_f32 v46, v34, v35
	v_cvt_pk_bf16_f32 v47, v36, v37
	v_add_f32_e32 v42, v52, v42
	global_store_dwordx4 v[48:49], v[44:47], off
	s_cbranch_execz .LBB0_437

.LBB0_432:
	v_lshlrev_b64 v[42:43], 10, v[132:133]
	v_lshl_add_u64 v[42:43], v[42:43], 0, v[194:195]
	v_lshl_add_u64 v[46:47], v[42:43], 0, s[22:23]
	s_andn2_b64 vcc, exec, s[42:43]
	v_lshl_add_u64 v[44:45], v[46:47], 2, s[72:73]
	s_cbranch_vccnz .LBB0_434
	s_waitcnt lgkmcnt(0)
	global_load_dwordx4 v[34:37], v[44:45], off offset:16
	global_load_dwordx4 v[38:41], v[44:45], off
	s_waitcnt vmcnt(0)
.LBB0_434:
	v_pk_add_f32 v[32:33], v[32:33], v[40:41]
	v_pk_add_f32 v[30:31], v[30:31], v[38:39]
	v_pk_add_f32 v[28:29], v[28:29], v[36:37]
	s_waitcnt lgkmcnt(0)
	v_pk_add_f32 v[26:27], v[26:27], v[34:35]
	s_mov_b64 s[42:43], -1
	s_and_b64 vcc, exec, s[6:7]
	s_cbranch_vccz .LBB0_441
	v_pk_mul_f32 v[34:35], v[32:33], v[32:33]
	v_pk_mul_f32 v[36:37], v[30:31], v[30:31]
	s_nop 0
	v_pk_mov_b32 v[38:39], v[36:37], v[34:35] op_sel:[1,0]
	v_mov_b32_e32 v37, v35
	v_pk_add_f32 v[34:35], v[38:39], v[36:37]
	v_pk_mul_f32 v[36:37], v[28:29], v[28:29]
	v_pk_mul_f32 v[38:39], v[26:27], v[26:27]
	v_mov_b32_e32 v40, v36
	v_mov_b32_e32 v41, v38
	v_mov_b32_e32 v38, v37
	v_pk_add_f32 v[36:37], v[40:41], v[38:39]
	v_add_f32_e32 v34, v34, v35
	v_add_f32_e32 v34, v34, v37
	v_add_f32_e32 v36, v36, v34
	v_lshl_add_u64 v[34:35], v[46:47], 1, s[28:29]
	v_cvt_pk_bf16_f32 v38, v30, v31
	v_cvt_pk_bf16_f32 v39, v32, v33
	v_cvt_pk_bf16_f32 v40, v26, v27
	v_cvt_pk_bf16_f32 v41, v28, v29
	global_store_dwordx4 v[34:35], v[38:41], off
	v_lshl_add_u64 v[34:35], v[46:47], 2, s[90:91]
	s_cbranch_execnz .LBB0_443
	s_branch .LBB0_442

.LBB0_446:
	global_load_dwordx4 v[26:29], v[44:45], off offset:528
	global_load_dwordx4 v[30:33], v[44:45], off offset:512
	s_waitcnt vmcnt(0)
.LBB0_447:
	v_pk_add_f32 v[24:25], v[24:25], v[32:33]
	v_pk_add_f32 v[22:23], v[22:23], v[30:31]
	v_pk_add_f32 v[20:21], v[20:21], v[28:29]
	v_pk_add_f32 v[18:19], v[18:19], v[26:27]
	s_mov_b64 s[42:43], -1
	s_and_b64 vcc, exec, s[6:7]
	s_cbranch_vccz .LBB0_456
	v_pk_mul_f32 v[26:27], v[24:25], v[24:25]
	v_pk_mul_f32 v[30:31], v[22:23], v[22:23]
	v_lshl_add_u64 v[28:29], v[42:43], 0, s[24:25]
	v_pk_mov_b32 v[32:33], v[30:31], v[26:27] op_sel:[1,0]
	v_mov_b32_e32 v31, v27
	v_pk_add_f32 v[26:27], v[32:33], v[30:31]
	v_pk_mul_f32 v[30:31], v[20:21], v[20:21]
	v_pk_mul_f32 v[32:33], v[18:19], v[18:19]
	v_mov_b32_e32 v38, v30
	v_mov_b32_e32 v39, v32
	v_mov_b32_e32 v32, v31
	v_pk_add_f32 v[30:31], v[38:39], v[32:33]
	v_add_f32_e32 v26, v26, v27
	v_add_f32_e32 v26, v26, v31
	v_add_f32_e32 v26, v30, v26
	v_lshl_add_u64 v[32:33], v[28:29], 1, s[28:29]
	v_cvt_pk_bf16_f32 v28, v22, v23
	v_cvt_pk_bf16_f32 v29, v24, v25
	v_cvt_pk_bf16_f32 v30, v18, v19
	v_cvt_pk_bf16_f32 v31, v20, v21
	v_add_f32_e32 v26, v36, v26
	global_store_dwordx4 v[32:33], v[28:31], off
	s_cbranch_execz .LBB0_457

.LBB0_452:
	v_lshlrev_b64 v[26:27], 10, v[130:131]
	v_lshl_add_u64 v[26:27], v[26:27], 0, v[194:195]
	v_lshl_add_u64 v[30:31], v[26:27], 0, s[22:23]
	s_andn2_b64 vcc, exec, s[42:43]
	v_lshl_add_u64 v[28:29], v[30:31], 2, s[72:73]
	s_cbranch_vccnz .LBB0_454
	s_waitcnt lgkmcnt(0)
	global_load_dwordx4 v[18:21], v[28:29], off offset:16
	global_load_dwordx4 v[22:25], v[28:29], off
	s_waitcnt vmcnt(0)
.LBB0_454:
	v_pk_add_f32 v[16:17], v[16:17], v[24:25]
	v_pk_add_f32 v[14:15], v[14:15], v[22:23]
	v_pk_add_f32 v[12:13], v[12:13], v[20:21]
	s_waitcnt lgkmcnt(0)
	v_pk_add_f32 v[10:11], v[10:11], v[18:19]
	s_mov_b64 s[22:23], -1
	s_and_b64 vcc, exec, s[6:7]
	s_cbranch_vccz .LBB0_461
	v_pk_mul_f32 v[18:19], v[16:17], v[16:17]
	v_pk_mul_f32 v[20:21], v[14:15], v[14:15]
	s_nop 0
	v_pk_mov_b32 v[22:23], v[20:21], v[18:19] op_sel:[1,0]
	v_mov_b32_e32 v21, v19
	v_pk_add_f32 v[18:19], v[22:23], v[20:21]
	v_pk_mul_f32 v[20:21], v[12:13], v[12:13]
	v_pk_mul_f32 v[22:23], v[10:11], v[10:11]
	v_mov_b32_e32 v24, v20
	v_mov_b32_e32 v25, v22
	v_mov_b32_e32 v22, v21
	v_pk_add_f32 v[20:21], v[24:25], v[22:23]
	v_add_f32_e32 v18, v18, v19
	v_add_f32_e32 v18, v18, v21
	v_add_f32_e32 v20, v20, v18
	v_lshl_add_u64 v[18:19], v[30:31], 1, s[28:29]
	v_cvt_pk_bf16_f32 v22, v14, v15
	v_cvt_pk_bf16_f32 v23, v16, v17
	v_cvt_pk_bf16_f32 v24, v10, v11
	v_cvt_pk_bf16_f32 v25, v12, v13
	global_store_dwordx4 v[18:19], v[22:25], off
	v_lshl_add_u64 v[18:19], v[30:31], 2, s[90:91]
	s_cbranch_execnz .LBB0_463
	s_branch .LBB0_462

.LBB0_466:
	global_load_dwordx4 v[10:13], v[28:29], off offset:528
	global_load_dwordx4 v[14:17], v[28:29], off offset:512
	s_waitcnt vmcnt(0)
.LBB0_467:
	v_pk_add_f32 v[8:9], v[8:9], v[16:17]
	v_pk_add_f32 v[6:7], v[6:7], v[14:15]
	v_pk_add_f32 v[4:5], v[4:5], v[12:13]
	v_pk_add_f32 v[2:3], v[2:3], v[10:11]
	s_mov_b64 s[22:23], -1
	s_and_b64 vcc, exec, s[6:7]
	s_cbranch_vccz .LBB0_473
	v_pk_mul_f32 v[10:11], v[8:9], v[8:9]
	v_pk_mul_f32 v[14:15], v[6:7], v[6:7]
	v_lshl_add_u64 v[12:13], v[26:27], 0, s[24:25]
	v_pk_mov_b32 v[16:17], v[14:15], v[10:11] op_sel:[1,0]
	v_mov_b32_e32 v15, v11
	v_pk_add_f32 v[10:11], v[16:17], v[14:15]
	v_pk_mul_f32 v[14:15], v[4:5], v[4:5]
	v_pk_mul_f32 v[16:17], v[2:3], v[2:3]
	v_mov_b32_e32 v22, v14
	v_mov_b32_e32 v23, v16
	v_mov_b32_e32 v16, v15
	v_pk_add_f32 v[14:15], v[22:23], v[16:17]
	v_add_f32_e32 v10, v10, v11
	v_add_f32_e32 v10, v10, v15
	v_add_f32_e32 v10, v14, v10
	v_lshl_add_u64 v[16:17], v[12:13], 1, s[28:29]
	v_cvt_pk_bf16_f32 v12, v6, v7
	v_cvt_pk_bf16_f32 v13, v8, v9
	v_cvt_pk_bf16_f32 v14, v2, v3
	v_cvt_pk_bf16_f32 v15, v4, v5
	v_add_f32_e32 v10, v20, v10
	global_store_dwordx4 v[16:17], v[12:15], off
	s_cbranch_execz .LBB0_474
